# RG-LRU mode-1 tile loop: the 32 conv-input ds_read_u16 issued up front instead of 16 dependent LDS round trips (on top of attention edits)
# speedup vs baseline: 1.0095x; 1.0061x over previous
; DI bf16_t f2bf(float a) { return (bf16_t)(pk2(a, 0.f) & 0xffffu); }
; DI float bf2f(unsigned b) { return __uint_as_float(b << 16); }
; DI void phase_lru(const Params& p, int layer, int b0, int nb, int mode, bool skipctx, char* smem) {
;     ...
;     if (mode == 1 && tid < 128) preh = H0[((size_t)(b * 2 + (tid >> 6)) * 68 + j) * 512 + nblk * 64 + (tid & 63)];
;     ...
;     __syncthreads();
; #pragma unroll
;     for (int i = 0; i < 8; ++i) {
;       const int tok = (tid >> 6) + 8 * i;
;       const float u = bb + w0 * bf2f(xs[tok * 64 + ch]) + w1 * bf2f(xs[(tok + 1) * 64 + ch]) + w2 * bf2f(xs[(tok + 2) * 64 + ch]) + w3 * bf2f(xs[(tok + 3) * 64 + ch]);
;       uF[tok * 64 + ch] = u; uA[tok * 72 + ch] = f2bf(u);
;     }
;     const float h0v = (mode == 1) ? h0s[sd * 64 + sch] : 0.f;
;     if (j + bpg < 68) issue(j + bpg);
.LBB0_821:
	s_mul_i32 s0, s42, 0x2200
	v_mov_b32_e32 v99, v192
	s_add_i32 s0, s0, 0
	s_waitcnt lgkmcnt(0)
	v_and_b32_e32 v75, 63, v99
	v_and_b32_e32 v1, 0x7fffffc0, v99
	v_lshlrev_b32_e32 v72, 1, v75
	v_lshl_add_u32 v2, v99, 1, s0
	v_lshlrev_b32_e32 v1, 1, v1
	s_barrier
	ds_read_u16 v134, v2
	ds_read_u16 v135, v2 offset:128
	ds_read_u16 v136, v2 offset:256
	ds_read_u16 v137, v2 offset:384
	ds_read_u16 v138, v2 offset:1024
	ds_read_u16 v139, v2 offset:1152
	ds_read_u16 v140, v2 offset:1280
	ds_read_u16 v141, v2 offset:1408
	ds_read_u16 v142, v2 offset:2048
	ds_read_u16 v143, v2 offset:2176
	ds_read_u16 v144, v2 offset:2304
	ds_read_u16 v145, v2 offset:2432
	ds_read_u16 v146, v2 offset:3072
	ds_read_u16 v147, v2 offset:3200
	ds_read_u16 v148, v2 offset:3328
	ds_read_u16 v149, v2 offset:3456
	ds_read_u16 v150, v2 offset:4096
	ds_read_u16 v151, v2 offset:4224
	ds_read_u16 v152, v2 offset:4352
	ds_read_u16 v153, v2 offset:4480
	ds_read_u16 v154, v2 offset:5120
	ds_read_u16 v155, v2 offset:5248
	ds_read_u16 v156, v2 offset:5376
	ds_read_u16 v157, v2 offset:5504
	ds_read_u16 v158, v2 offset:6144
	ds_read_u16 v159, v2 offset:6272
	ds_read_u16 v160, v2 offset:6400
	ds_read_u16 v161, v2 offset:6528
	ds_read_u16 v162, v2 offset:7168
	ds_read_u16 v163, v2 offset:7296
	ds_read_u16 v164, v2 offset:7424
	ds_read_u16 v165, v2 offset:7552
	v_ashrrev_i32_e32 v80, 6, v99
	v_lshl_add_u32 v100, v99, 2, 0
	v_add_u32_e32 v74, 8, v80
	v_add_u32_e32 v76, 16, v80
	v_add_u32_e32 v78, 24, v80
	v_add_u32_e32 v82, 32, v80
	v_add_u32_e32 v84, 40, v80
	v_add_u32_e32 v86, 48, v80
	v_add_u32_e32 v88, 56, v80
	v_and_b32_e32 v77, 15, v99
	v_lshlrev_b32_e32 v0, 4, v80
	v_and_or_b32 v87, v0, 48, v77
	v_lshlrev_b32_e32 v79, 2, v87
	v_and_b32_e32 v0, 0xffffff00, v99
	s_add_i32 s4, s13, s15
	v_mul_lo_u32 v175, v80, s21
	v_add3_u32 v175, 0, v72, v175
	s_waitcnt lgkmcnt(15)
	v_lshlrev_b32_e32 v134, 16, v134
	v_lshlrev_b32_e32 v135, 16, v135
	v_lshlrev_b32_e32 v136, 16, v136
	v_lshlrev_b32_e32 v137, 16, v137
	v_fma_f32 v166, v93, v134, v96
	v_fmac_f32_e32 v166, v94, v135
	v_fmac_f32_e32 v166, v95, v136
	v_fmac_f32_e32 v166, v97, v137
	ds_write_b32 v100, v166 offset:26624
	v_cvt_pk_bf16_f32 v174, v166, v166
	ds_write_b16 v175, v174 offset:17408
	s_waitcnt lgkmcnt(15)
	v_lshlrev_b32_e32 v138, 16, v138
	v_lshlrev_b32_e32 v139, 16, v139
	v_lshlrev_b32_e32 v140, 16, v140
	v_lshlrev_b32_e32 v141, 16, v141
	v_fma_f32 v167, v93, v138, v96
	v_fmac_f32_e32 v167, v94, v139
	v_fmac_f32_e32 v167, v95, v140
	v_fmac_f32_e32 v167, v97, v141
	ds_write_b32 v100, v167 offset:28672
	v_cvt_pk_bf16_f32 v174, v167, v167
	ds_write_b16 v175, v174 offset:18560
	s_waitcnt lgkmcnt(15)
	v_lshlrev_b32_e32 v142, 16, v142
	v_lshlrev_b32_e32 v143, 16, v143
	v_lshlrev_b32_e32 v144, 16, v144
	v_lshlrev_b32_e32 v145, 16, v145
	v_fma_f32 v168, v93, v142, v96
	v_fmac_f32_e32 v168, v94, v143
	v_fmac_f32_e32 v168, v95, v144
	v_fmac_f32_e32 v168, v97, v145
	ds_write_b32 v100, v168 offset:30720
	v_cvt_pk_bf16_f32 v174, v168, v168
	ds_write_b16 v175, v174 offset:19712
	s_waitcnt lgkmcnt(15)
	v_lshlrev_b32_e32 v146, 16, v146
	v_lshlrev_b32_e32 v147, 16, v147
	v_lshlrev_b32_e32 v148, 16, v148
	v_lshlrev_b32_e32 v149, 16, v149
	v_fma_f32 v169, v93, v146, v96
	v_fmac_f32_e32 v169, v94, v147
	v_fmac_f32_e32 v169, v95, v148
	v_fmac_f32_e32 v169, v97, v149
	ds_write_b32 v100, v169 offset:32768
	v_cvt_pk_bf16_f32 v174, v169, v169
	ds_write_b16 v175, v174 offset:20864
	s_waitcnt lgkmcnt(15)
	v_lshlrev_b32_e32 v150, 16, v150
	v_lshlrev_b32_e32 v151, 16, v151
	v_lshlrev_b32_e32 v152, 16, v152
	v_lshlrev_b32_e32 v153, 16, v153
	v_fma_f32 v170, v93, v150, v96
	v_fmac_f32_e32 v170, v94, v151
	v_fmac_f32_e32 v170, v95, v152
	v_fmac_f32_e32 v170, v97, v153
	ds_write_b32 v100, v170 offset:34816
	v_cvt_pk_bf16_f32 v174, v170, v170
	ds_write_b16 v175, v174 offset:22016
	s_waitcnt lgkmcnt(15)
	v_lshlrev_b32_e32 v154, 16, v154
	v_lshlrev_b32_e32 v155, 16, v155
	v_lshlrev_b32_e32 v156, 16, v156
	v_lshlrev_b32_e32 v157, 16, v157
	v_fma_f32 v171, v93, v154, v96
	v_fmac_f32_e32 v171, v94, v155
	v_fmac_f32_e32 v171, v95, v156
	v_fmac_f32_e32 v171, v97, v157
	ds_write_b32 v100, v171 offset:36864
	v_cvt_pk_bf16_f32 v174, v171, v171
	ds_write_b16 v175, v174 offset:23168
	s_waitcnt lgkmcnt(15)
	v_lshlrev_b32_e32 v158, 16, v158
	v_lshlrev_b32_e32 v159, 16, v159
	v_lshlrev_b32_e32 v160, 16, v160
	v_lshlrev_b32_e32 v161, 16, v161
	v_fma_f32 v172, v93, v158, v96
	v_fmac_f32_e32 v172, v94, v159
	v_fmac_f32_e32 v172, v95, v160
	v_fmac_f32_e32 v172, v97, v161
	ds_write_b32 v100, v172 offset:38912
	v_cvt_pk_bf16_f32 v174, v172, v172
	ds_write_b16 v175, v174 offset:24320
	s_waitcnt lgkmcnt(14)
	v_lshlrev_b32_e32 v162, 16, v162
	v_lshlrev_b32_e32 v163, 16, v163
	v_lshlrev_b32_e32 v164, 16, v164
	v_lshlrev_b32_e32 v165, 16, v165
	v_fma_f32 v173, v93, v162, v96
	v_fmac_f32_e32 v173, v94, v163
	v_fmac_f32_e32 v173, v95, v164
	v_fmac_f32_e32 v173, v97, v165
	ds_write_b32 v100, v173 offset:40960
	v_cvt_pk_bf16_f32 v174, v173, v173
	ds_write_b16 v175, v174 offset:25472
	s_add_i32 s0, 0, 0x1ac00
	v_add3_u32 v0, s0, v79, v0
	ds_read_b32 v83, v0
	s_movk_i32 s0, 0x80
	s_cmpk_gt_i32 s4, 0x43
	v_cmp_gt_i32_e32 vcc, s0, v99
	s_cbranch_scc1 .LBB0_829
	s_and_saveexec_b64 s[0:1], vcc
	s_cbranch_execz .LBB0_824
	s_ashr_i32 s5, s4, 31
	v_add_u32_e32 v2, s9, v80
	v_mov_b32_e32 v0, s4
	v_mov_b32_e32 v1, s5
	s_movk_i32 s5, 0x44
	v_mad_i64_i32 v[0:1], s[38:39], v2, s5, v[0:1]
	v_lshlrev_b64 v[0:1], 11, v[0:1]
	v_lshl_add_u64 v[0:1], s[36:37], 0, v[0:1]
	v_lshlrev_b32_e32 v220, 2, v75
	v_lshl_add_u64 v[0:1], v[0:1], 0, v[220:221]
	global_load_dword v98, v[0:1], off

; DI bf16_t f2bf(float a) { return (bf16_t)(pk2(a, 0.f) & 0xffffu); }
; DI float bf2f(unsigned b) { return __uint_as_float(b << 16); }
; DI void phase_lru(const Params& p, int layer, int b0, int nb, int mode, bool skipctx, char* smem) {
;     ...
;     if (mode == 1 && tid < 128) preh = H0[((size_t)(b * 2 + (tid >> 6)) * 68 + j) * 512 + nblk * 64 + (tid & 63)];
;     ...
;     __syncthreads();
; #pragma unroll
;     for (int i = 0; i < 8; ++i) {
;       const int tok = (tid >> 6) + 8 * i;
;       const float u = bb + w0 * bf2f(xs[tok * 64 + ch]) + w1 * bf2f(xs[(tok + 1) * 64 + ch]) + w2 * bf2f(xs[(tok + 2) * 64 + ch]) + w3 * bf2f(xs[(tok + 3) * 64 + ch]);
;       uF[tok * 64 + ch] = u; uA[tok * 72 + ch] = f2bf(u);
;     }
;     const float h0v = (mode == 1) ? h0s[sd * 64 + sch] : 0.f;
;     if (j + bpg < 68) issue(j + bpg);
.LBB0_1080:
	s_mul_i32 s0, s42, 0x2200
	v_mov_b32_e32 v99, v192
	s_add_i32 s0, s0, 0
	s_waitcnt lgkmcnt(0)
	v_and_b32_e32 v75, 63, v99
	v_and_b32_e32 v1, 0x7fffffc0, v99
	v_lshlrev_b32_e32 v72, 1, v75
	v_lshl_add_u32 v2, v99, 1, s0
	v_lshlrev_b32_e32 v1, 1, v1
	s_barrier
	ds_read_u16 v134, v2
	ds_read_u16 v135, v2 offset:128
	ds_read_u16 v136, v2 offset:256
	ds_read_u16 v137, v2 offset:384
	ds_read_u16 v138, v2 offset:1024
	ds_read_u16 v139, v2 offset:1152
	ds_read_u16 v140, v2 offset:1280
	ds_read_u16 v141, v2 offset:1408
	ds_read_u16 v142, v2 offset:2048
	ds_read_u16 v143, v2 offset:2176
	ds_read_u16 v144, v2 offset:2304
	ds_read_u16 v145, v2 offset:2432
	ds_read_u16 v146, v2 offset:3072
	ds_read_u16 v147, v2 offset:3200
	ds_read_u16 v148, v2 offset:3328
	ds_read_u16 v149, v2 offset:3456
	ds_read_u16 v150, v2 offset:4096
	ds_read_u16 v151, v2 offset:4224
	ds_read_u16 v152, v2 offset:4352
	ds_read_u16 v153, v2 offset:4480
	ds_read_u16 v154, v2 offset:5120
	ds_read_u16 v155, v2 offset:5248
	ds_read_u16 v156, v2 offset:5376
	ds_read_u16 v157, v2 offset:5504
	ds_read_u16 v158, v2 offset:6144
	ds_read_u16 v159, v2 offset:6272
	ds_read_u16 v160, v2 offset:6400
	ds_read_u16 v161, v2 offset:6528
	ds_read_u16 v162, v2 offset:7168
	ds_read_u16 v163, v2 offset:7296
	ds_read_u16 v164, v2 offset:7424
	ds_read_u16 v165, v2 offset:7552
	v_ashrrev_i32_e32 v80, 6, v99
	v_lshl_add_u32 v100, v99, 2, 0
	v_add_u32_e32 v74, 8, v80
	v_add_u32_e32 v76, 16, v80
	v_add_u32_e32 v78, 24, v80
	v_add_u32_e32 v82, 32, v80
	v_add_u32_e32 v84, 40, v80
	v_add_u32_e32 v86, 48, v80
	v_add_u32_e32 v88, 56, v80
	v_and_b32_e32 v77, 15, v99
	v_lshlrev_b32_e32 v0, 4, v80
	v_and_or_b32 v87, v0, 48, v77
	v_lshlrev_b32_e32 v79, 2, v87
	v_and_b32_e32 v0, 0xffffff00, v99
	s_add_i32 s4, s13, s15
	v_mul_lo_u32 v175, v80, s21
	v_add3_u32 v175, 0, v72, v175
	s_waitcnt lgkmcnt(15)
	v_lshlrev_b32_e32 v134, 16, v134
	v_lshlrev_b32_e32 v135, 16, v135
	v_lshlrev_b32_e32 v136, 16, v136
	v_lshlrev_b32_e32 v137, 16, v137
	v_fma_f32 v166, v93, v134, v96
	v_fmac_f32_e32 v166, v94, v135
	v_fmac_f32_e32 v166, v95, v136
	v_fmac_f32_e32 v166, v97, v137
	ds_write_b32 v100, v166 offset:26624
	v_cvt_pk_bf16_f32 v174, v166, v166
	ds_write_b16 v175, v174 offset:17408
	s_waitcnt lgkmcnt(15)
	v_lshlrev_b32_e32 v138, 16, v138
	v_lshlrev_b32_e32 v139, 16, v139
	v_lshlrev_b32_e32 v140, 16, v140
	v_lshlrev_b32_e32 v141, 16, v141
	v_fma_f32 v167, v93, v138, v96
	v_fmac_f32_e32 v167, v94, v139
	v_fmac_f32_e32 v167, v95, v140
	v_fmac_f32_e32 v167, v97, v141
	ds_write_b32 v100, v167 offset:28672
	v_cvt_pk_bf16_f32 v174, v167, v167
	ds_write_b16 v175, v174 offset:18560
	s_waitcnt lgkmcnt(15)
	v_lshlrev_b32_e32 v142, 16, v142
	v_lshlrev_b32_e32 v143, 16, v143
	v_lshlrev_b32_e32 v144, 16, v144
	v_lshlrev_b32_e32 v145, 16, v145
	v_fma_f32 v168, v93, v142, v96
	v_fmac_f32_e32 v168, v94, v143
	v_fmac_f32_e32 v168, v95, v144
	v_fmac_f32_e32 v168, v97, v145
	ds_write_b32 v100, v168 offset:30720
	v_cvt_pk_bf16_f32 v174, v168, v168
	ds_write_b16 v175, v174 offset:19712
	s_waitcnt lgkmcnt(15)
	v_lshlrev_b32_e32 v146, 16, v146
	v_lshlrev_b32_e32 v147, 16, v147
	v_lshlrev_b32_e32 v148, 16, v148
	v_lshlrev_b32_e32 v149, 16, v149
	v_fma_f32 v169, v93, v146, v96
	v_fmac_f32_e32 v169, v94, v147
	v_fmac_f32_e32 v169, v95, v148
	v_fmac_f32_e32 v169, v97, v149
	ds_write_b32 v100, v169 offset:32768
	v_cvt_pk_bf16_f32 v174, v169, v169
	ds_write_b16 v175, v174 offset:20864
	s_waitcnt lgkmcnt(15)
	v_lshlrev_b32_e32 v150, 16, v150
	v_lshlrev_b32_e32 v151, 16, v151
	v_lshlrev_b32_e32 v152, 16, v152
	v_lshlrev_b32_e32 v153, 16, v153
	v_fma_f32 v170, v93, v150, v96
	v_fmac_f32_e32 v170, v94, v151
	v_fmac_f32_e32 v170, v95, v152
	v_fmac_f32_e32 v170, v97, v153
	ds_write_b32 v100, v170 offset:34816
	v_cvt_pk_bf16_f32 v174, v170, v170
	ds_write_b16 v175, v174 offset:22016
	s_waitcnt lgkmcnt(15)
	v_lshlrev_b32_e32 v154, 16, v154
	v_lshlrev_b32_e32 v155, 16, v155
	v_lshlrev_b32_e32 v156, 16, v156
	v_lshlrev_b32_e32 v157, 16, v157
	v_fma_f32 v171, v93, v154, v96
	v_fmac_f32_e32 v171, v94, v155
	v_fmac_f32_e32 v171, v95, v156
	v_fmac_f32_e32 v171, v97, v157
	ds_write_b32 v100, v171 offset:36864
	v_cvt_pk_bf16_f32 v174, v171, v171
	ds_write_b16 v175, v174 offset:23168
	s_waitcnt lgkmcnt(15)
	v_lshlrev_b32_e32 v158, 16, v158
	v_lshlrev_b32_e32 v159, 16, v159
	v_lshlrev_b32_e32 v160, 16, v160
	v_lshlrev_b32_e32 v161, 16, v161
	v_fma_f32 v172, v93, v158, v96
	v_fmac_f32_e32 v172, v94, v159
	v_fmac_f32_e32 v172, v95, v160
	v_fmac_f32_e32 v172, v97, v161
	ds_write_b32 v100, v172 offset:38912
	v_cvt_pk_bf16_f32 v174, v172, v172
	ds_write_b16 v175, v174 offset:24320
	s_waitcnt lgkmcnt(14)
	v_lshlrev_b32_e32 v162, 16, v162
	v_lshlrev_b32_e32 v163, 16, v163
	v_lshlrev_b32_e32 v164, 16, v164
	v_lshlrev_b32_e32 v165, 16, v165
	v_fma_f32 v173, v93, v162, v96
	v_fmac_f32_e32 v173, v94, v163
	v_fmac_f32_e32 v173, v95, v164
	v_fmac_f32_e32 v173, v97, v165
	ds_write_b32 v100, v173 offset:40960
	v_cvt_pk_bf16_f32 v174, v173, v173
	ds_write_b16 v175, v174 offset:25472
	s_add_i32 s0, 0, 0x1ac00
	v_add3_u32 v0, s0, v79, v0
	ds_read_b32 v83, v0
	s_movk_i32 s0, 0x80
	s_cmpk_gt_i32 s4, 0x43
	v_cmp_gt_i32_e32 vcc, s0, v99
	s_cbranch_scc1 .LBB0_1088
	s_and_saveexec_b64 s[0:1], vcc
	s_cbranch_execz .LBB0_1083
	s_ashr_i32 s5, s4, 31
	v_add_u32_e32 v2, s9, v80
	v_mov_b32_e32 v0, s4
	v_mov_b32_e32 v1, s5
	s_movk_i32 s5, 0x44
	v_mad_i64_i32 v[0:1], s[38:39], v2, s5, v[0:1]
	v_lshlrev_b64 v[0:1], 11, v[0:1]
	v_lshl_add_u64 v[0:1], s[26:27], 0, v[0:1]
	v_lshlrev_b32_e32 v220, 2, v75
	v_lshl_add_u64 v[0:1], v[0:1], 0, v[220:221]
	global_load_dword v98, v[0:1], off
